# RW (f16) and GATE (sigmoid) GEMM epilogues as contiguous sixteen-block fast paths with dwordx4 stores via v_permlane16_swap
# speedup vs baseline: 1.0135x; 1.0135x over previous
.LBB0_90:
	v_mbcnt_lo_u32_b32 v200, -1, 0
	v_mbcnt_hi_u32_b32 v200, -1, v200
	v_and_b32_e32 v200, 16, v200
	v_lshrrev_b32_e32 v201, 1, v200
	v_add_u32_e32 v200, v200, v201
	v_mov_b32_e32 v201, 0
	v_mov_b32_e32 v136, s88
	ds_read_b32 v136, v136
	v_readlane_b32 s2, v254, 44
	v_mov_b32_e32 v151, v153
	s_mov_b64 s[58:59], -1
	s_mov_b64 s[56:57], 0
	s_waitcnt lgkmcnt(0)
	v_readfirstlane_b32 s48, v136
	v_mov_b32_e32 v136, s89
	ds_read_b32 v136, v136
	s_add_u32 s52, s48, 0x2100000
	s_waitcnt lgkmcnt(0)
	v_readfirstlane_b32 s49, v136
	v_mov_b32_e32 v136, s2
	ds_read_b32 v136, v136
	v_readlane_b32 s2, v254, 45
	s_addc_u32 s53, s49, 0
	s_add_u32 s46, s48, 0x158d0000
	s_addc_u32 s47, s49, 0
	s_waitcnt lgkmcnt(0)
	v_readfirstlane_b32 s42, v136
	v_mov_b32_e32 v136, s2
	ds_read_b32 v136, v136
	v_readlane_b32 s2, v254, 31
	s_add_u32 s40, s48, 0xc600000
	s_addc_u32 s41, s49, 0
	s_add_u32 s36, s48, 0xe700000
	s_waitcnt lgkmcnt(0)
	v_readfirstlane_b32 s43, v136
	v_mov_b32_e32 v136, s2
	ds_read_b32 v136, v136
	v_readlane_b32 s2, v254, 46
	s_addc_u32 s37, s49, 0
	s_add_u32 s34, s48, 0x6300000
	s_addc_u32 s35, s49, 0
	s_waitcnt lgkmcnt(0)
	v_readfirstlane_b32 s65, v136
	v_mov_b32_e32 v136, s2
	ds_read_b32 v136, v136
	v_readlane_b32 s2, v254, 39
	s_add_u32 s38, s48, 0x4200000
	s_addc_u32 s39, s49, 0
	s_add_u32 s50, s48, 0x15af4000
	s_waitcnt lgkmcnt(0)
	v_readfirstlane_b32 s66, v136
	v_mov_b32_e32 v136, s2
	ds_read_b32 v136, v136
	v_readlane_b32 s2, v254, 48
	s_addc_u32 s51, s49, 0
	s_lshl_b32 s62, s10, 8
	s_lshl_b32 s27, s67, 8
	s_waitcnt lgkmcnt(0)
	v_readfirstlane_b32 s44, v136
	v_mov_b32_e32 v136, s2
	v_readlane_b32 s2, v254, 40
	s_add_i32 s62, s62, s2
	s_ashr_i32 s2, s62, 13
	ds_read_b32 v136, v136
	s_mul_i32 s54, s2, 0x1800
	v_readlane_b32 s2, v254, 26
	s_ashr_i32 s55, s54, 31
	s_mul_i32 s2, s2, 0x12000
	s_add_u32 s2, s48, s2
	v_or_b32_e32 v138, s62, v157
	s_addc_u32 s3, s49, 0
	v_ashrrev_i32_e32 v139, 31, v138
	s_add_u32 s30, s2, 0x15ad0000
	s_waitcnt lgkmcnt(0)
	v_readfirstlane_b32 s45, v136
	v_lshlrev_b64 v[136:137], 13, v[138:139]
	v_add_u32_e32 v150, 0xffffc000, v138
	s_addc_u32 s31, s3, 0
	v_lshl_add_u64 v[148:149], s[52:53], 0, v[136:137]
	v_cmp_gt_i32_e64 s[10:11], s92, v138
	v_cmp_lt_i32_e64 s[8:9], s80, v138
	v_lshlrev_b64 v[146:147], 10, v[150:151]
	v_lshlrev_b64 v[142:143], 10, v[138:139]
	v_or_b32_e32 v136, s27, v161
	s_cmp_lg_u32 s79, 18
	s_cbranch_scc1 .Lrw_no
	v_lshlrev_b64 v[244:245], 11, v[138:139]
	v_lshl_add_u64 v[244:245], s[48:49], 0, v[244:245]
	v_mbcnt_lo_u32_b32 v246, -1, 0
	v_mbcnt_hi_u32_b32 v246, -1, v246
	v_and_b32_e32 v246, 16, v246
	v_lshrrev_b32_e32 v247, 1, v246
	v_add_u32_e32 v246, v246, v247
	v_and_b32_e32 v247, 0x3ff, v136
	v_lshl_add_u32 v246, v247, 1, v246
	v_mov_b32_e32 v247, 0
	v_lshl_add_u64 v[244:245], v[246:247], 0, v[244:245]
	s_ashr_i32 s2, s67, 2
	s_add_i32 s2, s2, 1
	s_mul_i32 s2, s2, 0x2100000
	s_mov_b32 s3, 0
	v_lshl_add_u64 v[244:245], v[244:245], 0, s[2:3]
	v_cvt_pk_f16_f32 v230, v124, v125
	v_cvt_pk_f16_f32 v231, v126, v127
	v_cvt_pk_f16_f32 v232, v120, v121
	v_cvt_pk_f16_f32 v233, v122, v123
	s_nop 1
	v_permlane16_swap_b32 v230, v232
	v_permlane16_swap_b32 v231, v233
	global_store_dwordx4 v[244:245], v[230:233], off
	v_cvt_pk_f16_f32 v234, v116, v117
	v_cvt_pk_f16_f32 v235, v118, v119
	v_cvt_pk_f16_f32 v236, v112, v113
	v_cvt_pk_f16_f32 v237, v114, v115
	v_add_co_u32_e32 v246, vcc, 0x100, v244
	v_addc_co_u32_e32 v247, vcc, 0, v245, vcc
	v_permlane16_swap_b32 v234, v236
	v_permlane16_swap_b32 v235, v237
	global_store_dwordx4 v[246:247], v[234:237], off
	v_cvt_pk_f16_f32 v230, v108, v109
	v_cvt_pk_f16_f32 v231, v110, v111
	v_cvt_pk_f16_f32 v232, v104, v105
	v_cvt_pk_f16_f32 v233, v106, v107
	v_add_co_u32_e32 v246, vcc, 0x8000, v244
	v_addc_co_u32_e32 v247, vcc, 0, v245, vcc
	v_permlane16_swap_b32 v230, v232
	v_permlane16_swap_b32 v231, v233
	global_store_dwordx4 v[246:247], v[230:233], off
	v_cvt_pk_f16_f32 v234, v100, v101
	v_cvt_pk_f16_f32 v235, v102, v103
	v_cvt_pk_f16_f32 v236, v96, v97
	v_cvt_pk_f16_f32 v237, v98, v99
	v_add_co_u32_e32 v246, vcc, 0x8100, v244
	v_addc_co_u32_e32 v247, vcc, 0, v245, vcc
	v_permlane16_swap_b32 v234, v236
	v_permlane16_swap_b32 v235, v237
	global_store_dwordx4 v[246:247], v[234:237], off
	v_cvt_pk_f16_f32 v230, v92, v93
	v_cvt_pk_f16_f32 v231, v94, v95
	v_cvt_pk_f16_f32 v232, v88, v89
	v_cvt_pk_f16_f32 v233, v90, v91
	v_add_co_u32_e32 v246, vcc, 0x10000, v244
	v_addc_co_u32_e32 v247, vcc, 0, v245, vcc
	v_permlane16_swap_b32 v230, v232
	v_permlane16_swap_b32 v231, v233
	global_store_dwordx4 v[246:247], v[230:233], off
	v_cvt_pk_f16_f32 v234, v84, v85
	v_cvt_pk_f16_f32 v235, v86, v87
	v_cvt_pk_f16_f32 v236, v80, v81
	v_cvt_pk_f16_f32 v237, v82, v83
	v_add_co_u32_e32 v246, vcc, 0x10100, v244
	v_addc_co_u32_e32 v247, vcc, 0, v245, vcc
	v_permlane16_swap_b32 v234, v236
	v_permlane16_swap_b32 v235, v237
	global_store_dwordx4 v[246:247], v[234:237], off
	v_cvt_pk_f16_f32 v230, v76, v77
	v_cvt_pk_f16_f32 v231, v78, v79
	v_cvt_pk_f16_f32 v232, v72, v73
	v_cvt_pk_f16_f32 v233, v74, v75
	v_add_co_u32_e32 v246, vcc, 0x18000, v244
	v_addc_co_u32_e32 v247, vcc, 0, v245, vcc
	v_permlane16_swap_b32 v230, v232
	v_permlane16_swap_b32 v231, v233
	global_store_dwordx4 v[246:247], v[230:233], off
	v_cvt_pk_f16_f32 v234, v68, v69
	v_cvt_pk_f16_f32 v235, v70, v71
	v_cvt_pk_f16_f32 v236, v64, v65
	v_cvt_pk_f16_f32 v237, v66, v67
	v_add_co_u32_e32 v246, vcc, 0x18100, v244
	v_addc_co_u32_e32 v247, vcc, 0, v245, vcc
	v_permlane16_swap_b32 v234, v236
	v_permlane16_swap_b32 v235, v237
	global_store_dwordx4 v[246:247], v[234:237], off
	v_cvt_pk_f16_f32 v230, v60, v61
	v_cvt_pk_f16_f32 v231, v62, v63
	v_cvt_pk_f16_f32 v232, v56, v57
	v_cvt_pk_f16_f32 v233, v58, v59
	v_add_co_u32_e32 v246, vcc, 0x40000, v244
	v_addc_co_u32_e32 v247, vcc, 0, v245, vcc
	v_permlane16_swap_b32 v230, v232
	v_permlane16_swap_b32 v231, v233
	global_store_dwordx4 v[246:247], v[230:233], off
	v_cvt_pk_f16_f32 v234, v52, v53
	v_cvt_pk_f16_f32 v235, v54, v55
	v_cvt_pk_f16_f32 v236, v48, v49
	v_cvt_pk_f16_f32 v237, v50, v51
	v_add_co_u32_e32 v246, vcc, 0x40100, v244
	v_addc_co_u32_e32 v247, vcc, 0, v245, vcc
	v_permlane16_swap_b32 v234, v236
	v_permlane16_swap_b32 v235, v237
	global_store_dwordx4 v[246:247], v[234:237], off
	v_cvt_pk_f16_f32 v230, v44, v45
	v_cvt_pk_f16_f32 v231, v46, v47
	v_cvt_pk_f16_f32 v232, v40, v41
	v_cvt_pk_f16_f32 v233, v42, v43
	v_add_co_u32_e32 v246, vcc, 0x48000, v244
	v_addc_co_u32_e32 v247, vcc, 0, v245, vcc
	v_permlane16_swap_b32 v230, v232
	v_permlane16_swap_b32 v231, v233
	global_store_dwordx4 v[246:247], v[230:233], off
	v_cvt_pk_f16_f32 v234, v36, v37
	v_cvt_pk_f16_f32 v235, v38, v39
	v_cvt_pk_f16_f32 v236, v32, v33
	v_cvt_pk_f16_f32 v237, v34, v35
	v_add_co_u32_e32 v246, vcc, 0x48100, v244
	v_addc_co_u32_e32 v247, vcc, 0, v245, vcc
	v_permlane16_swap_b32 v234, v236
	v_permlane16_swap_b32 v235, v237
	global_store_dwordx4 v[246:247], v[234:237], off
	v_cvt_pk_f16_f32 v230, v28, v29
	v_cvt_pk_f16_f32 v231, v30, v31
	v_cvt_pk_f16_f32 v232, v24, v25
	v_cvt_pk_f16_f32 v233, v26, v27
	v_add_co_u32_e32 v246, vcc, 0x50000, v244
	v_addc_co_u32_e32 v247, vcc, 0, v245, vcc
	v_permlane16_swap_b32 v230, v232
	v_permlane16_swap_b32 v231, v233
	global_store_dwordx4 v[246:247], v[230:233], off
	v_cvt_pk_f16_f32 v234, v20, v21
	v_cvt_pk_f16_f32 v235, v22, v23
	v_cvt_pk_f16_f32 v236, v16, v17
	v_cvt_pk_f16_f32 v237, v18, v19
	v_add_co_u32_e32 v246, vcc, 0x50100, v244
	v_addc_co_u32_e32 v247, vcc, 0, v245, vcc
	v_permlane16_swap_b32 v234, v236
	v_permlane16_swap_b32 v235, v237
	global_store_dwordx4 v[246:247], v[234:237], off
	v_cvt_pk_f16_f32 v230, v12, v13
	v_cvt_pk_f16_f32 v231, v14, v15
	v_cvt_pk_f16_f32 v232, v8, v9
	v_cvt_pk_f16_f32 v233, v10, v11
	v_add_co_u32_e32 v246, vcc, 0x58000, v244
	v_addc_co_u32_e32 v247, vcc, 0, v245, vcc
	v_permlane16_swap_b32 v230, v232
	v_permlane16_swap_b32 v231, v233
	global_store_dwordx4 v[246:247], v[230:233], off
	v_cvt_pk_f16_f32 v234, v4, v5
	v_cvt_pk_f16_f32 v235, v6, v7
	v_cvt_pk_f16_f32 v236, v0, v1
	v_cvt_pk_f16_f32 v237, v2, v3
	v_add_co_u32_e32 v246, vcc, 0x58100, v244
	v_addc_co_u32_e32 v247, vcc, 0, v245, vcc
	v_permlane16_swap_b32 v234, v236
	v_permlane16_swap_b32 v235, v237
	global_store_dwordx4 v[246:247], v[234:237], off
	s_branch .LBB0_1065
.Lrw_no:
	s_cmp_lg_u32 s79, 21
	s_cbranch_scc1 .Lgate_no
	v_lshlrev_b64 v[244:245], 11, v[138:139]
	v_lshl_add_u64 v[244:245], s[48:49], 0, v[244:245]
	v_mbcnt_lo_u32_b32 v246, -1, 0
	v_mbcnt_hi_u32_b32 v246, -1, v246
	v_and_b32_e32 v246, 16, v246
	v_lshrrev_b32_e32 v247, 1, v246
	v_add_u32_e32 v246, v246, v247
	v_and_b32_e32 v247, 0x3ff, v136
	v_lshl_add_u32 v246, v247, 1, v246
	v_mov_b32_e32 v247, 0
	v_lshl_add_u64 v[244:245], v[246:247], 0, v[244:245]
	s_and_b32 s2, s67, 0xfffffc
	s_cmp_eq_u32 s2, 4
	s_mov_b32 s2, 0x6300000
	s_cselect_b32 s2, s2, 0xc600000
	s_cmpk_gt_u32 s27, 0x3ff
	s_cselect_b32 s2, s2, 0x4200000
	s_mov_b32 s3, 0
	v_lshl_add_u64 v[244:245], v[244:245], 0, s[2:3]
	v_mul_f32_e32 v124, 0xbfb8aa3b, v124
	v_mul_f32_e32 v125, 0xbfb8aa3b, v125
	v_mul_f32_e32 v126, 0xbfb8aa3b, v126
	v_mul_f32_e32 v127, 0xbfb8aa3b, v127
	v_mul_f32_e32 v120, 0xbfb8aa3b, v120
	v_mul_f32_e32 v121, 0xbfb8aa3b, v121
	v_mul_f32_e32 v122, 0xbfb8aa3b, v122
	v_mul_f32_e32 v123, 0xbfb8aa3b, v123
	v_exp_f32_e32 v124, v124
	v_exp_f32_e32 v125, v125
	v_exp_f32_e32 v126, v126
	v_exp_f32_e32 v127, v127
	v_exp_f32_e32 v120, v120
	v_exp_f32_e32 v121, v121
	v_exp_f32_e32 v122, v122
	v_exp_f32_e32 v123, v123
	v_add_f32_e32 v124, 1.0, v124
	v_add_f32_e32 v125, 1.0, v125
	v_add_f32_e32 v126, 1.0, v126
	v_add_f32_e32 v127, 1.0, v127
	v_add_f32_e32 v120, 1.0, v120
	v_add_f32_e32 v121, 1.0, v121
	v_add_f32_e32 v122, 1.0, v122
	v_add_f32_e32 v123, 1.0, v123
	v_rcp_f32_e32 v124, v124
	v_rcp_f32_e32 v125, v125
	v_rcp_f32_e32 v126, v126
	v_rcp_f32_e32 v127, v127
	v_rcp_f32_e32 v120, v120
	v_rcp_f32_e32 v121, v121
	v_rcp_f32_e32 v122, v122
	v_rcp_f32_e32 v123, v123
	v_cvt_pk_bf16_f32 v230, v124, v125
	v_cvt_pk_bf16_f32 v231, v126, v127
	v_cvt_pk_bf16_f32 v232, v120, v121
	v_cvt_pk_bf16_f32 v233, v122, v123
	s_nop 1
	v_permlane16_swap_b32 v230, v232
	v_permlane16_swap_b32 v231, v233
	global_store_dwordx4 v[244:245], v[230:233], off
	v_mul_f32_e32 v116, 0xbfb8aa3b, v116
	v_mul_f32_e32 v117, 0xbfb8aa3b, v117
	v_mul_f32_e32 v118, 0xbfb8aa3b, v118
	v_mul_f32_e32 v119, 0xbfb8aa3b, v119
	v_mul_f32_e32 v112, 0xbfb8aa3b, v112
	v_mul_f32_e32 v113, 0xbfb8aa3b, v113
	v_mul_f32_e32 v114, 0xbfb8aa3b, v114
	v_mul_f32_e32 v115, 0xbfb8aa3b, v115
	v_exp_f32_e32 v116, v116
	v_exp_f32_e32 v117, v117
	v_exp_f32_e32 v118, v118
	v_exp_f32_e32 v119, v119
	v_exp_f32_e32 v112, v112
	v_exp_f32_e32 v113, v113
	v_exp_f32_e32 v114, v114
	v_exp_f32_e32 v115, v115
	v_add_f32_e32 v116, 1.0, v116
	v_add_f32_e32 v117, 1.0, v117
	v_add_f32_e32 v118, 1.0, v118
	v_add_f32_e32 v119, 1.0, v119
	v_add_f32_e32 v112, 1.0, v112
	v_add_f32_e32 v113, 1.0, v113
	v_add_f32_e32 v114, 1.0, v114
	v_add_f32_e32 v115, 1.0, v115
	v_rcp_f32_e32 v116, v116
	v_rcp_f32_e32 v117, v117
	v_rcp_f32_e32 v118, v118
	v_rcp_f32_e32 v119, v119
	v_rcp_f32_e32 v112, v112
	v_rcp_f32_e32 v113, v113
	v_rcp_f32_e32 v114, v114
	v_rcp_f32_e32 v115, v115
	v_cvt_pk_bf16_f32 v234, v116, v117
	v_cvt_pk_bf16_f32 v235, v118, v119
	v_cvt_pk_bf16_f32 v236, v112, v113
	v_cvt_pk_bf16_f32 v237, v114, v115
	v_add_co_u32_e32 v246, vcc, 0x100, v244
	v_addc_co_u32_e32 v247, vcc, 0, v245, vcc
	v_permlane16_swap_b32 v234, v236
	v_permlane16_swap_b32 v235, v237
	global_store_dwordx4 v[246:247], v[234:237], off
	v_mul_f32_e32 v108, 0xbfb8aa3b, v108
	v_mul_f32_e32 v109, 0xbfb8aa3b, v109
	v_mul_f32_e32 v110, 0xbfb8aa3b, v110
	v_mul_f32_e32 v111, 0xbfb8aa3b, v111
	v_mul_f32_e32 v104, 0xbfb8aa3b, v104
	v_mul_f32_e32 v105, 0xbfb8aa3b, v105
	v_mul_f32_e32 v106, 0xbfb8aa3b, v106
	v_mul_f32_e32 v107, 0xbfb8aa3b, v107
	v_exp_f32_e32 v108, v108
	v_exp_f32_e32 v109, v109
	v_exp_f32_e32 v110, v110
	v_exp_f32_e32 v111, v111
	v_exp_f32_e32 v104, v104
	v_exp_f32_e32 v105, v105
	v_exp_f32_e32 v106, v106
	v_exp_f32_e32 v107, v107
	v_add_f32_e32 v108, 1.0, v108
	v_add_f32_e32 v109, 1.0, v109
	v_add_f32_e32 v110, 1.0, v110
	v_add_f32_e32 v111, 1.0, v111
	v_add_f32_e32 v104, 1.0, v104
	v_add_f32_e32 v105, 1.0, v105
	v_add_f32_e32 v106, 1.0, v106
	v_add_f32_e32 v107, 1.0, v107
	v_rcp_f32_e32 v108, v108
	v_rcp_f32_e32 v109, v109
	v_rcp_f32_e32 v110, v110
	v_rcp_f32_e32 v111, v111
	v_rcp_f32_e32 v104, v104
	v_rcp_f32_e32 v105, v105
	v_rcp_f32_e32 v106, v106
	v_rcp_f32_e32 v107, v107
	v_cvt_pk_bf16_f32 v230, v108, v109
	v_cvt_pk_bf16_f32 v231, v110, v111
	v_cvt_pk_bf16_f32 v232, v104, v105
	v_cvt_pk_bf16_f32 v233, v106, v107
	v_add_co_u32_e32 v246, vcc, 0x8000, v244
	v_addc_co_u32_e32 v247, vcc, 0, v245, vcc
	v_permlane16_swap_b32 v230, v232
	v_permlane16_swap_b32 v231, v233
	global_store_dwordx4 v[246:247], v[230:233], off
	v_mul_f32_e32 v100, 0xbfb8aa3b, v100
	v_mul_f32_e32 v101, 0xbfb8aa3b, v101
	v_mul_f32_e32 v102, 0xbfb8aa3b, v102
	v_mul_f32_e32 v103, 0xbfb8aa3b, v103
	v_mul_f32_e32 v96, 0xbfb8aa3b, v96
	v_mul_f32_e32 v97, 0xbfb8aa3b, v97
	v_mul_f32_e32 v98, 0xbfb8aa3b, v98
	v_mul_f32_e32 v99, 0xbfb8aa3b, v99
	v_exp_f32_e32 v100, v100
	v_exp_f32_e32 v101, v101
	v_exp_f32_e32 v102, v102
	v_exp_f32_e32 v103, v103
	v_exp_f32_e32 v96, v96
	v_exp_f32_e32 v97, v97
	v_exp_f32_e32 v98, v98
	v_exp_f32_e32 v99, v99
	v_add_f32_e32 v100, 1.0, v100
	v_add_f32_e32 v101, 1.0, v101
	v_add_f32_e32 v102, 1.0, v102
	v_add_f32_e32 v103, 1.0, v103
	v_add_f32_e32 v96, 1.0, v96
	v_add_f32_e32 v97, 1.0, v97
	v_add_f32_e32 v98, 1.0, v98
	v_add_f32_e32 v99, 1.0, v99
	v_rcp_f32_e32 v100, v100
	v_rcp_f32_e32 v101, v101
	v_rcp_f32_e32 v102, v102
	v_rcp_f32_e32 v103, v103
	v_rcp_f32_e32 v96, v96
	v_rcp_f32_e32 v97, v97
	v_rcp_f32_e32 v98, v98
	v_rcp_f32_e32 v99, v99
	v_cvt_pk_bf16_f32 v234, v100, v101
	v_cvt_pk_bf16_f32 v235, v102, v103
	v_cvt_pk_bf16_f32 v236, v96, v97
	v_cvt_pk_bf16_f32 v237, v98, v99
	v_add_co_u32_e32 v246, vcc, 0x8100, v244
	v_addc_co_u32_e32 v247, vcc, 0, v245, vcc
	v_permlane16_swap_b32 v234, v236
	v_permlane16_swap_b32 v235, v237
	global_store_dwordx4 v[246:247], v[234:237], off
	v_mul_f32_e32 v92, 0xbfb8aa3b, v92
	v_mul_f32_e32 v93, 0xbfb8aa3b, v93
	v_mul_f32_e32 v94, 0xbfb8aa3b, v94
	v_mul_f32_e32 v95, 0xbfb8aa3b, v95
	v_mul_f32_e32 v88, 0xbfb8aa3b, v88
	v_mul_f32_e32 v89, 0xbfb8aa3b, v89
	v_mul_f32_e32 v90, 0xbfb8aa3b, v90
	v_mul_f32_e32 v91, 0xbfb8aa3b, v91
	v_exp_f32_e32 v92, v92
	v_exp_f32_e32 v93, v93
	v_exp_f32_e32 v94, v94
	v_exp_f32_e32 v95, v95
	v_exp_f32_e32 v88, v88
	v_exp_f32_e32 v89, v89
	v_exp_f32_e32 v90, v90
	v_exp_f32_e32 v91, v91
	v_add_f32_e32 v92, 1.0, v92
	v_add_f32_e32 v93, 1.0, v93
	v_add_f32_e32 v94, 1.0, v94
	v_add_f32_e32 v95, 1.0, v95
	v_add_f32_e32 v88, 1.0, v88
	v_add_f32_e32 v89, 1.0, v89
	v_add_f32_e32 v90, 1.0, v90
	v_add_f32_e32 v91, 1.0, v91
	v_rcp_f32_e32 v92, v92
	v_rcp_f32_e32 v93, v93
	v_rcp_f32_e32 v94, v94
	v_rcp_f32_e32 v95, v95
	v_rcp_f32_e32 v88, v88
	v_rcp_f32_e32 v89, v89
	v_rcp_f32_e32 v90, v90
	v_rcp_f32_e32 v91, v91
	v_cvt_pk_bf16_f32 v230, v92, v93
	v_cvt_pk_bf16_f32 v231, v94, v95
	v_cvt_pk_bf16_f32 v232, v88, v89
	v_cvt_pk_bf16_f32 v233, v90, v91
	v_add_co_u32_e32 v246, vcc, 0x10000, v244
	v_addc_co_u32_e32 v247, vcc, 0, v245, vcc
	v_permlane16_swap_b32 v230, v232
	v_permlane16_swap_b32 v231, v233
	global_store_dwordx4 v[246:247], v[230:233], off
	v_mul_f32_e32 v84, 0xbfb8aa3b, v84
	v_mul_f32_e32 v85, 0xbfb8aa3b, v85
	v_mul_f32_e32 v86, 0xbfb8aa3b, v86
	v_mul_f32_e32 v87, 0xbfb8aa3b, v87
	v_mul_f32_e32 v80, 0xbfb8aa3b, v80
	v_mul_f32_e32 v81, 0xbfb8aa3b, v81
	v_mul_f32_e32 v82, 0xbfb8aa3b, v82
	v_mul_f32_e32 v83, 0xbfb8aa3b, v83
	v_exp_f32_e32 v84, v84
	v_exp_f32_e32 v85, v85
	v_exp_f32_e32 v86, v86
	v_exp_f32_e32 v87, v87
	v_exp_f32_e32 v80, v80
	v_exp_f32_e32 v81, v81
	v_exp_f32_e32 v82, v82
	v_exp_f32_e32 v83, v83
	v_add_f32_e32 v84, 1.0, v84
	v_add_f32_e32 v85, 1.0, v85
	v_add_f32_e32 v86, 1.0, v86
	v_add_f32_e32 v87, 1.0, v87
	v_add_f32_e32 v80, 1.0, v80
	v_add_f32_e32 v81, 1.0, v81
	v_add_f32_e32 v82, 1.0, v82
	v_add_f32_e32 v83, 1.0, v83
	v_rcp_f32_e32 v84, v84
	v_rcp_f32_e32 v85, v85
	v_rcp_f32_e32 v86, v86
	v_rcp_f32_e32 v87, v87
	v_rcp_f32_e32 v80, v80
	v_rcp_f32_e32 v81, v81
	v_rcp_f32_e32 v82, v82
	v_rcp_f32_e32 v83, v83
	v_cvt_pk_bf16_f32 v234, v84, v85
	v_cvt_pk_bf16_f32 v235, v86, v87
	v_cvt_pk_bf16_f32 v236, v80, v81
	v_cvt_pk_bf16_f32 v237, v82, v83
	v_add_co_u32_e32 v246, vcc, 0x10100, v244
	v_addc_co_u32_e32 v247, vcc, 0, v245, vcc
	v_permlane16_swap_b32 v234, v236
	v_permlane16_swap_b32 v235, v237
	global_store_dwordx4 v[246:247], v[234:237], off
	v_mul_f32_e32 v76, 0xbfb8aa3b, v76
	v_mul_f32_e32 v77, 0xbfb8aa3b, v77
	v_mul_f32_e32 v78, 0xbfb8aa3b, v78
	v_mul_f32_e32 v79, 0xbfb8aa3b, v79
	v_mul_f32_e32 v72, 0xbfb8aa3b, v72
	v_mul_f32_e32 v73, 0xbfb8aa3b, v73
	v_mul_f32_e32 v74, 0xbfb8aa3b, v74
	v_mul_f32_e32 v75, 0xbfb8aa3b, v75
	v_exp_f32_e32 v76, v76
	v_exp_f32_e32 v77, v77
	v_exp_f32_e32 v78, v78
	v_exp_f32_e32 v79, v79
	v_exp_f32_e32 v72, v72
	v_exp_f32_e32 v73, v73
	v_exp_f32_e32 v74, v74
	v_exp_f32_e32 v75, v75
	v_add_f32_e32 v76, 1.0, v76
	v_add_f32_e32 v77, 1.0, v77
	v_add_f32_e32 v78, 1.0, v78
	v_add_f32_e32 v79, 1.0, v79
	v_add_f32_e32 v72, 1.0, v72
	v_add_f32_e32 v73, 1.0, v73
	v_add_f32_e32 v74, 1.0, v74
	v_add_f32_e32 v75, 1.0, v75
	v_rcp_f32_e32 v76, v76
	v_rcp_f32_e32 v77, v77
	v_rcp_f32_e32 v78, v78
	v_rcp_f32_e32 v79, v79
	v_rcp_f32_e32 v72, v72
	v_rcp_f32_e32 v73, v73
	v_rcp_f32_e32 v74, v74
	v_rcp_f32_e32 v75, v75
	v_cvt_pk_bf16_f32 v230, v76, v77
	v_cvt_pk_bf16_f32 v231, v78, v79
	v_cvt_pk_bf16_f32 v232, v72, v73
	v_cvt_pk_bf16_f32 v233, v74, v75
	v_add_co_u32_e32 v246, vcc, 0x18000, v244
	v_addc_co_u32_e32 v247, vcc, 0, v245, vcc
	v_permlane16_swap_b32 v230, v232
	v_permlane16_swap_b32 v231, v233
	global_store_dwordx4 v[246:247], v[230:233], off
	v_mul_f32_e32 v68, 0xbfb8aa3b, v68
	v_mul_f32_e32 v69, 0xbfb8aa3b, v69
	v_mul_f32_e32 v70, 0xbfb8aa3b, v70
	v_mul_f32_e32 v71, 0xbfb8aa3b, v71
	v_mul_f32_e32 v64, 0xbfb8aa3b, v64
	v_mul_f32_e32 v65, 0xbfb8aa3b, v65
	v_mul_f32_e32 v66, 0xbfb8aa3b, v66
	v_mul_f32_e32 v67, 0xbfb8aa3b, v67
	v_exp_f32_e32 v68, v68
	v_exp_f32_e32 v69, v69
	v_exp_f32_e32 v70, v70
	v_exp_f32_e32 v71, v71
	v_exp_f32_e32 v64, v64
	v_exp_f32_e32 v65, v65
	v_exp_f32_e32 v66, v66
	v_exp_f32_e32 v67, v67
	v_add_f32_e32 v68, 1.0, v68
	v_add_f32_e32 v69, 1.0, v69
	v_add_f32_e32 v70, 1.0, v70
	v_add_f32_e32 v71, 1.0, v71
	v_add_f32_e32 v64, 1.0, v64
	v_add_f32_e32 v65, 1.0, v65
	v_add_f32_e32 v66, 1.0, v66
	v_add_f32_e32 v67, 1.0, v67
	v_rcp_f32_e32 v68, v68
	v_rcp_f32_e32 v69, v69
	v_rcp_f32_e32 v70, v70
	v_rcp_f32_e32 v71, v71
	v_rcp_f32_e32 v64, v64
	v_rcp_f32_e32 v65, v65
	v_rcp_f32_e32 v66, v66
	v_rcp_f32_e32 v67, v67
	v_cvt_pk_bf16_f32 v234, v68, v69
	v_cvt_pk_bf16_f32 v235, v70, v71
	v_cvt_pk_bf16_f32 v236, v64, v65
	v_cvt_pk_bf16_f32 v237, v66, v67
	v_add_co_u32_e32 v246, vcc, 0x18100, v244
	v_addc_co_u32_e32 v247, vcc, 0, v245, vcc
	v_permlane16_swap_b32 v234, v236
	v_permlane16_swap_b32 v235, v237
	global_store_dwordx4 v[246:247], v[234:237], off
	v_mul_f32_e32 v60, 0xbfb8aa3b, v60
	v_mul_f32_e32 v61, 0xbfb8aa3b, v61
	v_mul_f32_e32 v62, 0xbfb8aa3b, v62
	v_mul_f32_e32 v63, 0xbfb8aa3b, v63
	v_mul_f32_e32 v56, 0xbfb8aa3b, v56
	v_mul_f32_e32 v57, 0xbfb8aa3b, v57
	v_mul_f32_e32 v58, 0xbfb8aa3b, v58
	v_mul_f32_e32 v59, 0xbfb8aa3b, v59
	v_exp_f32_e32 v60, v60
	v_exp_f32_e32 v61, v61
	v_exp_f32_e32 v62, v62
	v_exp_f32_e32 v63, v63
	v_exp_f32_e32 v56, v56
	v_exp_f32_e32 v57, v57
	v_exp_f32_e32 v58, v58
	v_exp_f32_e32 v59, v59
	v_add_f32_e32 v60, 1.0, v60
	v_add_f32_e32 v61, 1.0, v61
	v_add_f32_e32 v62, 1.0, v62
	v_add_f32_e32 v63, 1.0, v63
	v_add_f32_e32 v56, 1.0, v56
	v_add_f32_e32 v57, 1.0, v57
	v_add_f32_e32 v58, 1.0, v58
	v_add_f32_e32 v59, 1.0, v59
	v_rcp_f32_e32 v60, v60
	v_rcp_f32_e32 v61, v61
	v_rcp_f32_e32 v62, v62
	v_rcp_f32_e32 v63, v63
	v_rcp_f32_e32 v56, v56
	v_rcp_f32_e32 v57, v57
	v_rcp_f32_e32 v58, v58
	v_rcp_f32_e32 v59, v59
	v_cvt_pk_bf16_f32 v230, v60, v61
	v_cvt_pk_bf16_f32 v231, v62, v63
	v_cvt_pk_bf16_f32 v232, v56, v57
	v_cvt_pk_bf16_f32 v233, v58, v59
	v_add_co_u32_e32 v246, vcc, 0x40000, v244
	v_addc_co_u32_e32 v247, vcc, 0, v245, vcc
	v_permlane16_swap_b32 v230, v232
	v_permlane16_swap_b32 v231, v233
	global_store_dwordx4 v[246:247], v[230:233], off
	v_mul_f32_e32 v52, 0xbfb8aa3b, v52
	v_mul_f32_e32 v53, 0xbfb8aa3b, v53
	v_mul_f32_e32 v54, 0xbfb8aa3b, v54
	v_mul_f32_e32 v55, 0xbfb8aa3b, v55
	v_mul_f32_e32 v48, 0xbfb8aa3b, v48
	v_mul_f32_e32 v49, 0xbfb8aa3b, v49
	v_mul_f32_e32 v50, 0xbfb8aa3b, v50
	v_mul_f32_e32 v51, 0xbfb8aa3b, v51
	v_exp_f32_e32 v52, v52
	v_exp_f32_e32 v53, v53
	v_exp_f32_e32 v54, v54
	v_exp_f32_e32 v55, v55
	v_exp_f32_e32 v48, v48
	v_exp_f32_e32 v49, v49
	v_exp_f32_e32 v50, v50
	v_exp_f32_e32 v51, v51
	v_add_f32_e32 v52, 1.0, v52
	v_add_f32_e32 v53, 1.0, v53
	v_add_f32_e32 v54, 1.0, v54
	v_add_f32_e32 v55, 1.0, v55
	v_add_f32_e32 v48, 1.0, v48
	v_add_f32_e32 v49, 1.0, v49
	v_add_f32_e32 v50, 1.0, v50
	v_add_f32_e32 v51, 1.0, v51
	v_rcp_f32_e32 v52, v52
	v_rcp_f32_e32 v53, v53
	v_rcp_f32_e32 v54, v54
	v_rcp_f32_e32 v55, v55
	v_rcp_f32_e32 v48, v48
	v_rcp_f32_e32 v49, v49
	v_rcp_f32_e32 v50, v50
	v_rcp_f32_e32 v51, v51
	v_cvt_pk_bf16_f32 v234, v52, v53
	v_cvt_pk_bf16_f32 v235, v54, v55
	v_cvt_pk_bf16_f32 v236, v48, v49
	v_cvt_pk_bf16_f32 v237, v50, v51
	v_add_co_u32_e32 v246, vcc, 0x40100, v244
	v_addc_co_u32_e32 v247, vcc, 0, v245, vcc
	v_permlane16_swap_b32 v234, v236
	v_permlane16_swap_b32 v235, v237
	global_store_dwordx4 v[246:247], v[234:237], off
	v_mul_f32_e32 v44, 0xbfb8aa3b, v44
	v_mul_f32_e32 v45, 0xbfb8aa3b, v45
	v_mul_f32_e32 v46, 0xbfb8aa3b, v46
	v_mul_f32_e32 v47, 0xbfb8aa3b, v47
	v_mul_f32_e32 v40, 0xbfb8aa3b, v40
	v_mul_f32_e32 v41, 0xbfb8aa3b, v41
	v_mul_f32_e32 v42, 0xbfb8aa3b, v42
	v_mul_f32_e32 v43, 0xbfb8aa3b, v43
	v_exp_f32_e32 v44, v44
	v_exp_f32_e32 v45, v45
	v_exp_f32_e32 v46, v46
	v_exp_f32_e32 v47, v47
	v_exp_f32_e32 v40, v40
	v_exp_f32_e32 v41, v41
	v_exp_f32_e32 v42, v42
	v_exp_f32_e32 v43, v43
	v_add_f32_e32 v44, 1.0, v44
	v_add_f32_e32 v45, 1.0, v45
	v_add_f32_e32 v46, 1.0, v46
	v_add_f32_e32 v47, 1.0, v47
	v_add_f32_e32 v40, 1.0, v40
	v_add_f32_e32 v41, 1.0, v41
	v_add_f32_e32 v42, 1.0, v42
	v_add_f32_e32 v43, 1.0, v43
	v_rcp_f32_e32 v44, v44
	v_rcp_f32_e32 v45, v45
	v_rcp_f32_e32 v46, v46
	v_rcp_f32_e32 v47, v47
	v_rcp_f32_e32 v40, v40
	v_rcp_f32_e32 v41, v41
	v_rcp_f32_e32 v42, v42
	v_rcp_f32_e32 v43, v43
	v_cvt_pk_bf16_f32 v230, v44, v45
	v_cvt_pk_bf16_f32 v231, v46, v47
	v_cvt_pk_bf16_f32 v232, v40, v41
	v_cvt_pk_bf16_f32 v233, v42, v43
	v_add_co_u32_e32 v246, vcc, 0x48000, v244
	v_addc_co_u32_e32 v247, vcc, 0, v245, vcc
	v_permlane16_swap_b32 v230, v232
	v_permlane16_swap_b32 v231, v233
	global_store_dwordx4 v[246:247], v[230:233], off
	v_mul_f32_e32 v36, 0xbfb8aa3b, v36
	v_mul_f32_e32 v37, 0xbfb8aa3b, v37
	v_mul_f32_e32 v38, 0xbfb8aa3b, v38
	v_mul_f32_e32 v39, 0xbfb8aa3b, v39
	v_mul_f32_e32 v32, 0xbfb8aa3b, v32
	v_mul_f32_e32 v33, 0xbfb8aa3b, v33
	v_mul_f32_e32 v34, 0xbfb8aa3b, v34
	v_mul_f32_e32 v35, 0xbfb8aa3b, v35
	v_exp_f32_e32 v36, v36
	v_exp_f32_e32 v37, v37
	v_exp_f32_e32 v38, v38
	v_exp_f32_e32 v39, v39
	v_exp_f32_e32 v32, v32
	v_exp_f32_e32 v33, v33
	v_exp_f32_e32 v34, v34
	v_exp_f32_e32 v35, v35
	v_add_f32_e32 v36, 1.0, v36
	v_add_f32_e32 v37, 1.0, v37
	v_add_f32_e32 v38, 1.0, v38
	v_add_f32_e32 v39, 1.0, v39
	v_add_f32_e32 v32, 1.0, v32
	v_add_f32_e32 v33, 1.0, v33
	v_add_f32_e32 v34, 1.0, v34
	v_add_f32_e32 v35, 1.0, v35
	v_rcp_f32_e32 v36, v36
	v_rcp_f32_e32 v37, v37
	v_rcp_f32_e32 v38, v38
	v_rcp_f32_e32 v39, v39
	v_rcp_f32_e32 v32, v32
	v_rcp_f32_e32 v33, v33
	v_rcp_f32_e32 v34, v34
	v_rcp_f32_e32 v35, v35
	v_cvt_pk_bf16_f32 v234, v36, v37
	v_cvt_pk_bf16_f32 v235, v38, v39
	v_cvt_pk_bf16_f32 v236, v32, v33
	v_cvt_pk_bf16_f32 v237, v34, v35
	v_add_co_u32_e32 v246, vcc, 0x48100, v244
	v_addc_co_u32_e32 v247, vcc, 0, v245, vcc
	v_permlane16_swap_b32 v234, v236
	v_permlane16_swap_b32 v235, v237
	global_store_dwordx4 v[246:247], v[234:237], off
	v_mul_f32_e32 v28, 0xbfb8aa3b, v28
	v_mul_f32_e32 v29, 0xbfb8aa3b, v29
	v_mul_f32_e32 v30, 0xbfb8aa3b, v30
	v_mul_f32_e32 v31, 0xbfb8aa3b, v31
	v_mul_f32_e32 v24, 0xbfb8aa3b, v24
	v_mul_f32_e32 v25, 0xbfb8aa3b, v25
	v_mul_f32_e32 v26, 0xbfb8aa3b, v26
	v_mul_f32_e32 v27, 0xbfb8aa3b, v27
	v_exp_f32_e32 v28, v28
	v_exp_f32_e32 v29, v29
	v_exp_f32_e32 v30, v30
	v_exp_f32_e32 v31, v31
	v_exp_f32_e32 v24, v24
	v_exp_f32_e32 v25, v25
	v_exp_f32_e32 v26, v26
	v_exp_f32_e32 v27, v27
	v_add_f32_e32 v28, 1.0, v28
	v_add_f32_e32 v29, 1.0, v29
	v_add_f32_e32 v30, 1.0, v30
	v_add_f32_e32 v31, 1.0, v31
	v_add_f32_e32 v24, 1.0, v24
	v_add_f32_e32 v25, 1.0, v25
	v_add_f32_e32 v26, 1.0, v26
	v_add_f32_e32 v27, 1.0, v27
	v_rcp_f32_e32 v28, v28
	v_rcp_f32_e32 v29, v29
	v_rcp_f32_e32 v30, v30
	v_rcp_f32_e32 v31, v31
	v_rcp_f32_e32 v24, v24
	v_rcp_f32_e32 v25, v25
	v_rcp_f32_e32 v26, v26
	v_rcp_f32_e32 v27, v27
	v_cvt_pk_bf16_f32 v230, v28, v29
	v_cvt_pk_bf16_f32 v231, v30, v31
	v_cvt_pk_bf16_f32 v232, v24, v25
	v_cvt_pk_bf16_f32 v233, v26, v27
	v_add_co_u32_e32 v246, vcc, 0x50000, v244
	v_addc_co_u32_e32 v247, vcc, 0, v245, vcc
	v_permlane16_swap_b32 v230, v232
	v_permlane16_swap_b32 v231, v233
	global_store_dwordx4 v[246:247], v[230:233], off
	v_mul_f32_e32 v20, 0xbfb8aa3b, v20
	v_mul_f32_e32 v21, 0xbfb8aa3b, v21
	v_mul_f32_e32 v22, 0xbfb8aa3b, v22
	v_mul_f32_e32 v23, 0xbfb8aa3b, v23
	v_mul_f32_e32 v16, 0xbfb8aa3b, v16
	v_mul_f32_e32 v17, 0xbfb8aa3b, v17
	v_mul_f32_e32 v18, 0xbfb8aa3b, v18
	v_mul_f32_e32 v19, 0xbfb8aa3b, v19
	v_exp_f32_e32 v20, v20
	v_exp_f32_e32 v21, v21
	v_exp_f32_e32 v22, v22
	v_exp_f32_e32 v23, v23
	v_exp_f32_e32 v16, v16
	v_exp_f32_e32 v17, v17
	v_exp_f32_e32 v18, v18
	v_exp_f32_e32 v19, v19
	v_add_f32_e32 v20, 1.0, v20
	v_add_f32_e32 v21, 1.0, v21
	v_add_f32_e32 v22, 1.0, v22
	v_add_f32_e32 v23, 1.0, v23
	v_add_f32_e32 v16, 1.0, v16
	v_add_f32_e32 v17, 1.0, v17
	v_add_f32_e32 v18, 1.0, v18
	v_add_f32_e32 v19, 1.0, v19
	v_rcp_f32_e32 v20, v20
	v_rcp_f32_e32 v21, v21
	v_rcp_f32_e32 v22, v22
	v_rcp_f32_e32 v23, v23
	v_rcp_f32_e32 v16, v16
	v_rcp_f32_e32 v17, v17
	v_rcp_f32_e32 v18, v18
	v_rcp_f32_e32 v19, v19
	v_cvt_pk_bf16_f32 v234, v20, v21
	v_cvt_pk_bf16_f32 v235, v22, v23
	v_cvt_pk_bf16_f32 v236, v16, v17
	v_cvt_pk_bf16_f32 v237, v18, v19
	v_add_co_u32_e32 v246, vcc, 0x50100, v244
	v_addc_co_u32_e32 v247, vcc, 0, v245, vcc
	v_permlane16_swap_b32 v234, v236
	v_permlane16_swap_b32 v235, v237
	global_store_dwordx4 v[246:247], v[234:237], off
	v_mul_f32_e32 v12, 0xbfb8aa3b, v12
	v_mul_f32_e32 v13, 0xbfb8aa3b, v13
	v_mul_f32_e32 v14, 0xbfb8aa3b, v14
	v_mul_f32_e32 v15, 0xbfb8aa3b, v15
	v_mul_f32_e32 v8, 0xbfb8aa3b, v8
	v_mul_f32_e32 v9, 0xbfb8aa3b, v9
	v_mul_f32_e32 v10, 0xbfb8aa3b, v10
	v_mul_f32_e32 v11, 0xbfb8aa3b, v11
	v_exp_f32_e32 v12, v12
	v_exp_f32_e32 v13, v13
	v_exp_f32_e32 v14, v14
	v_exp_f32_e32 v15, v15
	v_exp_f32_e32 v8, v8
	v_exp_f32_e32 v9, v9
	v_exp_f32_e32 v10, v10
	v_exp_f32_e32 v11, v11
	v_add_f32_e32 v12, 1.0, v12
	v_add_f32_e32 v13, 1.0, v13
	v_add_f32_e32 v14, 1.0, v14
	v_add_f32_e32 v15, 1.0, v15
	v_add_f32_e32 v8, 1.0, v8
	v_add_f32_e32 v9, 1.0, v9
	v_add_f32_e32 v10, 1.0, v10
	v_add_f32_e32 v11, 1.0, v11
	v_rcp_f32_e32 v12, v12
	v_rcp_f32_e32 v13, v13
	v_rcp_f32_e32 v14, v14
	v_rcp_f32_e32 v15, v15
	v_rcp_f32_e32 v8, v8
	v_rcp_f32_e32 v9, v9
	v_rcp_f32_e32 v10, v10
	v_rcp_f32_e32 v11, v11
	v_cvt_pk_bf16_f32 v230, v12, v13
	v_cvt_pk_bf16_f32 v231, v14, v15
	v_cvt_pk_bf16_f32 v232, v8, v9
	v_cvt_pk_bf16_f32 v233, v10, v11
	v_add_co_u32_e32 v246, vcc, 0x58000, v244
	v_addc_co_u32_e32 v247, vcc, 0, v245, vcc
	v_permlane16_swap_b32 v230, v232
	v_permlane16_swap_b32 v231, v233
	global_store_dwordx4 v[246:247], v[230:233], off
	v_mul_f32_e32 v4, 0xbfb8aa3b, v4
	v_mul_f32_e32 v5, 0xbfb8aa3b, v5
	v_mul_f32_e32 v6, 0xbfb8aa3b, v6
	v_mul_f32_e32 v7, 0xbfb8aa3b, v7
	v_mul_f32_e32 v0, 0xbfb8aa3b, v0
	v_mul_f32_e32 v1, 0xbfb8aa3b, v1
	v_mul_f32_e32 v2, 0xbfb8aa3b, v2
	v_mul_f32_e32 v3, 0xbfb8aa3b, v3
	v_exp_f32_e32 v4, v4
	v_exp_f32_e32 v5, v5
	v_exp_f32_e32 v6, v6
	v_exp_f32_e32 v7, v7
	v_exp_f32_e32 v0, v0
	v_exp_f32_e32 v1, v1
	v_exp_f32_e32 v2, v2
	v_exp_f32_e32 v3, v3
	v_add_f32_e32 v4, 1.0, v4
	v_add_f32_e32 v5, 1.0, v5
	v_add_f32_e32 v6, 1.0, v6
	v_add_f32_e32 v7, 1.0, v7
	v_add_f32_e32 v0, 1.0, v0
	v_add_f32_e32 v1, 1.0, v1
	v_add_f32_e32 v2, 1.0, v2
	v_add_f32_e32 v3, 1.0, v3
	v_rcp_f32_e32 v4, v4
	v_rcp_f32_e32 v5, v5
	v_rcp_f32_e32 v6, v6
	v_rcp_f32_e32 v7, v7
	v_rcp_f32_e32 v0, v0
	v_rcp_f32_e32 v1, v1
	v_rcp_f32_e32 v2, v2
	v_rcp_f32_e32 v3, v3
	v_cvt_pk_bf16_f32 v234, v4, v5
	v_cvt_pk_bf16_f32 v235, v6, v7
	v_cvt_pk_bf16_f32 v236, v0, v1
	v_cvt_pk_bf16_f32 v237, v2, v3
	v_add_co_u32_e32 v246, vcc, 0x58100, v244
	v_addc_co_u32_e32 v247, vcc, 0, v245, vcc
	v_permlane16_swap_b32 v234, v236
	v_permlane16_swap_b32 v235, v237
	global_store_dwordx4 v[246:247], v[234:237], off
	s_branch .LBB0_1065
.Lgate_no:
	s_cmp_lg_u32 s79, 26
	s_cbranch_scc1 .Lff1_no
	v_ashrrev_i32_e32 v137, 31, v136
	v_lshl_add_u64 v[244:245], v[136:137], 1, v[148:149]
	v_mbcnt_lo_u32_b32 v246, -1, 0
	v_mbcnt_hi_u32_b32 v246, -1, v246
	v_and_b32_e32 v246, 16, v246
	v_lshrrev_b32_e32 v247, 1, v246
	v_add_u32_e32 v246, v246, v247
	v_mov_b32_e32 v247, 0
	v_lshl_add_u64 v[244:245], v[246:247], 0, v[244:245]
	v_max_f32_e32 v124, v124, v124
	v_max_f32_e32 v124, 0, v124
	v_mul_f32_e32 v124, v124, v124
	v_max_f32_e32 v125, v125, v125
	v_max_f32_e32 v125, 0, v125
	v_mul_f32_e32 v125, v125, v125
	v_max_f32_e32 v126, v126, v126
	v_max_f32_e32 v126, 0, v126
	v_mul_f32_e32 v126, v126, v126
	v_max_f32_e32 v127, v127, v127
	v_max_f32_e32 v127, 0, v127
	v_mul_f32_e32 v127, v127, v127
	v_max_f32_e32 v120, v120, v120
	v_max_f32_e32 v120, 0, v120
	v_mul_f32_e32 v120, v120, v120
	v_max_f32_e32 v121, v121, v121
	v_max_f32_e32 v121, 0, v121
	v_mul_f32_e32 v121, v121, v121
	v_max_f32_e32 v122, v122, v122
	v_max_f32_e32 v122, 0, v122
	v_mul_f32_e32 v122, v122, v122
	v_max_f32_e32 v123, v123, v123
	v_max_f32_e32 v123, 0, v123
	v_mul_f32_e32 v123, v123, v123
	v_cvt_pk_bf16_f32 v230, v124, v125
	v_cvt_pk_bf16_f32 v231, v126, v127
	v_cvt_pk_bf16_f32 v232, v120, v121
	v_cvt_pk_bf16_f32 v233, v122, v123
	s_nop 1
	v_permlane16_swap_b32 v230, v232
	v_permlane16_swap_b32 v231, v233
	global_store_dwordx4 v[244:245], v[230:233], off
	v_max_f32_e32 v116, v116, v116
	v_max_f32_e32 v116, 0, v116
	v_mul_f32_e32 v116, v116, v116
	v_max_f32_e32 v117, v117, v117
	v_max_f32_e32 v117, 0, v117
	v_mul_f32_e32 v117, v117, v117
	v_max_f32_e32 v118, v118, v118
	v_max_f32_e32 v118, 0, v118
	v_mul_f32_e32 v118, v118, v118
	v_max_f32_e32 v119, v119, v119
	v_max_f32_e32 v119, 0, v119
	v_mul_f32_e32 v119, v119, v119
	v_max_f32_e32 v112, v112, v112
	v_max_f32_e32 v112, 0, v112
	v_mul_f32_e32 v112, v112, v112
	v_max_f32_e32 v113, v113, v113
	v_max_f32_e32 v113, 0, v113
	v_mul_f32_e32 v113, v113, v113
	v_max_f32_e32 v114, v114, v114
	v_max_f32_e32 v114, 0, v114
	v_mul_f32_e32 v114, v114, v114
	v_max_f32_e32 v115, v115, v115
	v_max_f32_e32 v115, 0, v115
	v_mul_f32_e32 v115, v115, v115
	v_cvt_pk_bf16_f32 v234, v116, v117
	v_cvt_pk_bf16_f32 v235, v118, v119
	v_cvt_pk_bf16_f32 v236, v112, v113
	v_cvt_pk_bf16_f32 v237, v114, v115
	v_add_co_u32_e32 v246, vcc, 0x100, v244
	v_addc_co_u32_e32 v247, vcc, 0, v245, vcc
	v_permlane16_swap_b32 v234, v236
	v_permlane16_swap_b32 v235, v237
	global_store_dwordx4 v[246:247], v[234:237], off
	v_max_f32_e32 v108, v108, v108
	v_max_f32_e32 v108, 0, v108
	v_mul_f32_e32 v108, v108, v108
	v_max_f32_e32 v109, v109, v109
	v_max_f32_e32 v109, 0, v109
	v_mul_f32_e32 v109, v109, v109
	v_max_f32_e32 v110, v110, v110
	v_max_f32_e32 v110, 0, v110
	v_mul_f32_e32 v110, v110, v110
	v_max_f32_e32 v111, v111, v111
	v_max_f32_e32 v111, 0, v111
	v_mul_f32_e32 v111, v111, v111
	v_max_f32_e32 v104, v104, v104
	v_max_f32_e32 v104, 0, v104
	v_mul_f32_e32 v104, v104, v104
	v_max_f32_e32 v105, v105, v105
	v_max_f32_e32 v105, 0, v105
	v_mul_f32_e32 v105, v105, v105
	v_max_f32_e32 v106, v106, v106
	v_max_f32_e32 v106, 0, v106
	v_mul_f32_e32 v106, v106, v106
	v_max_f32_e32 v107, v107, v107
	v_max_f32_e32 v107, 0, v107
	v_mul_f32_e32 v107, v107, v107
	v_cvt_pk_bf16_f32 v230, v108, v109
	v_cvt_pk_bf16_f32 v231, v110, v111
	v_cvt_pk_bf16_f32 v232, v104, v105
	v_cvt_pk_bf16_f32 v233, v106, v107
	v_add_co_u32_e32 v246, vcc, 0x20000, v244
	v_addc_co_u32_e32 v247, vcc, 0, v245, vcc
	v_permlane16_swap_b32 v230, v232
	v_permlane16_swap_b32 v231, v233
	global_store_dwordx4 v[246:247], v[230:233], off
	v_max_f32_e32 v100, v100, v100
	v_max_f32_e32 v100, 0, v100
	v_mul_f32_e32 v100, v100, v100
	v_max_f32_e32 v101, v101, v101
	v_max_f32_e32 v101, 0, v101
	v_mul_f32_e32 v101, v101, v101
	v_max_f32_e32 v102, v102, v102
	v_max_f32_e32 v102, 0, v102
	v_mul_f32_e32 v102, v102, v102
	v_max_f32_e32 v103, v103, v103
	v_max_f32_e32 v103, 0, v103
	v_mul_f32_e32 v103, v103, v103
	v_max_f32_e32 v96, v96, v96
	v_max_f32_e32 v96, 0, v96
	v_mul_f32_e32 v96, v96, v96
	v_max_f32_e32 v97, v97, v97
	v_max_f32_e32 v97, 0, v97
	v_mul_f32_e32 v97, v97, v97
	v_max_f32_e32 v98, v98, v98
	v_max_f32_e32 v98, 0, v98
	v_mul_f32_e32 v98, v98, v98
	v_max_f32_e32 v99, v99, v99
	v_max_f32_e32 v99, 0, v99
	v_mul_f32_e32 v99, v99, v99
	v_cvt_pk_bf16_f32 v234, v100, v101
	v_cvt_pk_bf16_f32 v235, v102, v103
	v_cvt_pk_bf16_f32 v236, v96, v97
	v_cvt_pk_bf16_f32 v237, v98, v99
	v_add_co_u32_e32 v246, vcc, 0x20100, v244
	v_addc_co_u32_e32 v247, vcc, 0, v245, vcc
	v_permlane16_swap_b32 v234, v236
	v_permlane16_swap_b32 v235, v237
	global_store_dwordx4 v[246:247], v[234:237], off
	v_max_f32_e32 v92, v92, v92
	v_max_f32_e32 v92, 0, v92
	v_mul_f32_e32 v92, v92, v92
	v_max_f32_e32 v93, v93, v93
	v_max_f32_e32 v93, 0, v93
	v_mul_f32_e32 v93, v93, v93
	v_max_f32_e32 v94, v94, v94
	v_max_f32_e32 v94, 0, v94
	v_mul_f32_e32 v94, v94, v94
	v_max_f32_e32 v95, v95, v95
	v_max_f32_e32 v95, 0, v95
	v_mul_f32_e32 v95, v95, v95
	v_max_f32_e32 v88, v88, v88
	v_max_f32_e32 v88, 0, v88
	v_mul_f32_e32 v88, v88, v88
	v_max_f32_e32 v89, v89, v89
	v_max_f32_e32 v89, 0, v89
	v_mul_f32_e32 v89, v89, v89
	v_max_f32_e32 v90, v90, v90
	v_max_f32_e32 v90, 0, v90
	v_mul_f32_e32 v90, v90, v90
	v_max_f32_e32 v91, v91, v91
	v_max_f32_e32 v91, 0, v91
	v_mul_f32_e32 v91, v91, v91
	v_cvt_pk_bf16_f32 v230, v92, v93
	v_cvt_pk_bf16_f32 v231, v94, v95
	v_cvt_pk_bf16_f32 v232, v88, v89
	v_cvt_pk_bf16_f32 v233, v90, v91
	v_add_co_u32_e32 v246, vcc, 0x40000, v244
	v_addc_co_u32_e32 v247, vcc, 0, v245, vcc
	v_permlane16_swap_b32 v230, v232
	v_permlane16_swap_b32 v231, v233
	global_store_dwordx4 v[246:247], v[230:233], off
	v_max_f32_e32 v84, v84, v84
	v_max_f32_e32 v84, 0, v84
	v_mul_f32_e32 v84, v84, v84
	v_max_f32_e32 v85, v85, v85
	v_max_f32_e32 v85, 0, v85
	v_mul_f32_e32 v85, v85, v85
	v_max_f32_e32 v86, v86, v86
	v_max_f32_e32 v86, 0, v86
	v_mul_f32_e32 v86, v86, v86
	v_max_f32_e32 v87, v87, v87
	v_max_f32_e32 v87, 0, v87
	v_mul_f32_e32 v87, v87, v87
	v_max_f32_e32 v80, v80, v80
	v_max_f32_e32 v80, 0, v80
	v_mul_f32_e32 v80, v80, v80
	v_max_f32_e32 v81, v81, v81
	v_max_f32_e32 v81, 0, v81
	v_mul_f32_e32 v81, v81, v81
	v_max_f32_e32 v82, v82, v82
	v_max_f32_e32 v82, 0, v82
	v_mul_f32_e32 v82, v82, v82
	v_max_f32_e32 v83, v83, v83
	v_max_f32_e32 v83, 0, v83
	v_mul_f32_e32 v83, v83, v83
	v_cvt_pk_bf16_f32 v234, v84, v85
	v_cvt_pk_bf16_f32 v235, v86, v87
	v_cvt_pk_bf16_f32 v236, v80, v81
	v_cvt_pk_bf16_f32 v237, v82, v83
	v_add_co_u32_e32 v246, vcc, 0x40100, v244
	v_addc_co_u32_e32 v247, vcc, 0, v245, vcc
	v_permlane16_swap_b32 v234, v236
	v_permlane16_swap_b32 v235, v237
	global_store_dwordx4 v[246:247], v[234:237], off
	v_max_f32_e32 v76, v76, v76
	v_max_f32_e32 v76, 0, v76
	v_mul_f32_e32 v76, v76, v76
	v_max_f32_e32 v77, v77, v77
	v_max_f32_e32 v77, 0, v77
	v_mul_f32_e32 v77, v77, v77
	v_max_f32_e32 v78, v78, v78
	v_max_f32_e32 v78, 0, v78
	v_mul_f32_e32 v78, v78, v78
	v_max_f32_e32 v79, v79, v79
	v_max_f32_e32 v79, 0, v79
	v_mul_f32_e32 v79, v79, v79
	v_max_f32_e32 v72, v72, v72
	v_max_f32_e32 v72, 0, v72
	v_mul_f32_e32 v72, v72, v72
	v_max_f32_e32 v73, v73, v73
	v_max_f32_e32 v73, 0, v73
	v_mul_f32_e32 v73, v73, v73
	v_max_f32_e32 v74, v74, v74
	v_max_f32_e32 v74, 0, v74
	v_mul_f32_e32 v74, v74, v74
	v_max_f32_e32 v75, v75, v75
	v_max_f32_e32 v75, 0, v75
	v_mul_f32_e32 v75, v75, v75
	v_cvt_pk_bf16_f32 v230, v76, v77
	v_cvt_pk_bf16_f32 v231, v78, v79
	v_cvt_pk_bf16_f32 v232, v72, v73
	v_cvt_pk_bf16_f32 v233, v74, v75
	v_add_co_u32_e32 v246, vcc, 0x60000, v244
	v_addc_co_u32_e32 v247, vcc, 0, v245, vcc
	v_permlane16_swap_b32 v230, v232
	v_permlane16_swap_b32 v231, v233
	global_store_dwordx4 v[246:247], v[230:233], off
	v_max_f32_e32 v68, v68, v68
	v_max_f32_e32 v68, 0, v68
	v_mul_f32_e32 v68, v68, v68
	v_max_f32_e32 v69, v69, v69
	v_max_f32_e32 v69, 0, v69
	v_mul_f32_e32 v69, v69, v69
	v_max_f32_e32 v70, v70, v70
	v_max_f32_e32 v70, 0, v70
	v_mul_f32_e32 v70, v70, v70
	v_max_f32_e32 v71, v71, v71
	v_max_f32_e32 v71, 0, v71
	v_mul_f32_e32 v71, v71, v71
	v_max_f32_e32 v64, v64, v64
	v_max_f32_e32 v64, 0, v64
	v_mul_f32_e32 v64, v64, v64
	v_max_f32_e32 v65, v65, v65
	v_max_f32_e32 v65, 0, v65
	v_mul_f32_e32 v65, v65, v65
	v_max_f32_e32 v66, v66, v66
	v_max_f32_e32 v66, 0, v66
	v_mul_f32_e32 v66, v66, v66
	v_max_f32_e32 v67, v67, v67
	v_max_f32_e32 v67, 0, v67
	v_mul_f32_e32 v67, v67, v67
	v_cvt_pk_bf16_f32 v234, v68, v69
	v_cvt_pk_bf16_f32 v235, v70, v71
	v_cvt_pk_bf16_f32 v236, v64, v65
	v_cvt_pk_bf16_f32 v237, v66, v67
	v_add_co_u32_e32 v246, vcc, 0x60100, v244
	v_addc_co_u32_e32 v247, vcc, 0, v245, vcc
	v_permlane16_swap_b32 v234, v236
	v_permlane16_swap_b32 v235, v237
	global_store_dwordx4 v[246:247], v[234:237], off
	v_max_f32_e32 v60, v60, v60
	v_max_f32_e32 v60, 0, v60
	v_mul_f32_e32 v60, v60, v60
	v_max_f32_e32 v61, v61, v61
	v_max_f32_e32 v61, 0, v61
	v_mul_f32_e32 v61, v61, v61
	v_max_f32_e32 v62, v62, v62
	v_max_f32_e32 v62, 0, v62
	v_mul_f32_e32 v62, v62, v62
	v_max_f32_e32 v63, v63, v63
	v_max_f32_e32 v63, 0, v63
	v_mul_f32_e32 v63, v63, v63
	v_max_f32_e32 v56, v56, v56
	v_max_f32_e32 v56, 0, v56
	v_mul_f32_e32 v56, v56, v56
	v_max_f32_e32 v57, v57, v57
	v_max_f32_e32 v57, 0, v57
	v_mul_f32_e32 v57, v57, v57
	v_max_f32_e32 v58, v58, v58
	v_max_f32_e32 v58, 0, v58
	v_mul_f32_e32 v58, v58, v58
	v_max_f32_e32 v59, v59, v59
	v_max_f32_e32 v59, 0, v59
	v_mul_f32_e32 v59, v59, v59
	v_cvt_pk_bf16_f32 v230, v60, v61
	v_cvt_pk_bf16_f32 v231, v62, v63
	v_cvt_pk_bf16_f32 v232, v56, v57
	v_cvt_pk_bf16_f32 v233, v58, v59
	v_add_co_u32_e32 v246, vcc, 0x100000, v244
	v_addc_co_u32_e32 v247, vcc, 0, v245, vcc
	v_permlane16_swap_b32 v230, v232
	v_permlane16_swap_b32 v231, v233
	global_store_dwordx4 v[246:247], v[230:233], off
	v_max_f32_e32 v52, v52, v52
	v_max_f32_e32 v52, 0, v52
	v_mul_f32_e32 v52, v52, v52
	v_max_f32_e32 v53, v53, v53
	v_max_f32_e32 v53, 0, v53
	v_mul_f32_e32 v53, v53, v53
	v_max_f32_e32 v54, v54, v54
	v_max_f32_e32 v54, 0, v54
	v_mul_f32_e32 v54, v54, v54
	v_max_f32_e32 v55, v55, v55
	v_max_f32_e32 v55, 0, v55
	v_mul_f32_e32 v55, v55, v55
	v_max_f32_e32 v48, v48, v48
	v_max_f32_e32 v48, 0, v48
	v_mul_f32_e32 v48, v48, v48
	v_max_f32_e32 v49, v49, v49
	v_max_f32_e32 v49, 0, v49
	v_mul_f32_e32 v49, v49, v49
	v_max_f32_e32 v50, v50, v50
	v_max_f32_e32 v50, 0, v50
	v_mul_f32_e32 v50, v50, v50
	v_max_f32_e32 v51, v51, v51
	v_max_f32_e32 v51, 0, v51
	v_mul_f32_e32 v51, v51, v51
	v_cvt_pk_bf16_f32 v234, v52, v53
	v_cvt_pk_bf16_f32 v235, v54, v55
	v_cvt_pk_bf16_f32 v236, v48, v49
	v_cvt_pk_bf16_f32 v237, v50, v51
	v_add_co_u32_e32 v246, vcc, 0x100100, v244
	v_addc_co_u32_e32 v247, vcc, 0, v245, vcc
	v_permlane16_swap_b32 v234, v236
	v_permlane16_swap_b32 v235, v237
	global_store_dwordx4 v[246:247], v[234:237], off
	v_max_f32_e32 v44, v44, v44
	v_max_f32_e32 v44, 0, v44
	v_mul_f32_e32 v44, v44, v44
	v_max_f32_e32 v45, v45, v45
	v_max_f32_e32 v45, 0, v45
	v_mul_f32_e32 v45, v45, v45
	v_max_f32_e32 v46, v46, v46
	v_max_f32_e32 v46, 0, v46
	v_mul_f32_e32 v46, v46, v46
	v_max_f32_e32 v47, v47, v47
	v_max_f32_e32 v47, 0, v47
	v_mul_f32_e32 v47, v47, v47
	v_max_f32_e32 v40, v40, v40
	v_max_f32_e32 v40, 0, v40
	v_mul_f32_e32 v40, v40, v40
	v_max_f32_e32 v41, v41, v41
	v_max_f32_e32 v41, 0, v41
	v_mul_f32_e32 v41, v41, v41
	v_max_f32_e32 v42, v42, v42
	v_max_f32_e32 v42, 0, v42
	v_mul_f32_e32 v42, v42, v42
	v_max_f32_e32 v43, v43, v43
	v_max_f32_e32 v43, 0, v43
	v_mul_f32_e32 v43, v43, v43
	v_cvt_pk_bf16_f32 v230, v44, v45
	v_cvt_pk_bf16_f32 v231, v46, v47
	v_cvt_pk_bf16_f32 v232, v40, v41
	v_cvt_pk_bf16_f32 v233, v42, v43
	v_add_co_u32_e32 v246, vcc, 0x120000, v244
	v_addc_co_u32_e32 v247, vcc, 0, v245, vcc
	v_permlane16_swap_b32 v230, v232
	v_permlane16_swap_b32 v231, v233
	global_store_dwordx4 v[246:247], v[230:233], off
	v_max_f32_e32 v36, v36, v36
	v_max_f32_e32 v36, 0, v36
	v_mul_f32_e32 v36, v36, v36
	v_max_f32_e32 v37, v37, v37
	v_max_f32_e32 v37, 0, v37
	v_mul_f32_e32 v37, v37, v37
	v_max_f32_e32 v38, v38, v38
	v_max_f32_e32 v38, 0, v38
	v_mul_f32_e32 v38, v38, v38
	v_max_f32_e32 v39, v39, v39
	v_max_f32_e32 v39, 0, v39
	v_mul_f32_e32 v39, v39, v39
	v_max_f32_e32 v32, v32, v32
	v_max_f32_e32 v32, 0, v32
	v_mul_f32_e32 v32, v32, v32
	v_max_f32_e32 v33, v33, v33
	v_max_f32_e32 v33, 0, v33
	v_mul_f32_e32 v33, v33, v33
	v_max_f32_e32 v34, v34, v34
	v_max_f32_e32 v34, 0, v34
	v_mul_f32_e32 v34, v34, v34
	v_max_f32_e32 v35, v35, v35
	v_max_f32_e32 v35, 0, v35
	v_mul_f32_e32 v35, v35, v35
	v_cvt_pk_bf16_f32 v234, v36, v37
	v_cvt_pk_bf16_f32 v235, v38, v39
	v_cvt_pk_bf16_f32 v236, v32, v33
	v_cvt_pk_bf16_f32 v237, v34, v35
	v_add_co_u32_e32 v246, vcc, 0x120100, v244
	v_addc_co_u32_e32 v247, vcc, 0, v245, vcc
	v_permlane16_swap_b32 v234, v236
	v_permlane16_swap_b32 v235, v237
	global_store_dwordx4 v[246:247], v[234:237], off
	v_max_f32_e32 v28, v28, v28
	v_max_f32_e32 v28, 0, v28
	v_mul_f32_e32 v28, v28, v28
	v_max_f32_e32 v29, v29, v29
	v_max_f32_e32 v29, 0, v29
	v_mul_f32_e32 v29, v29, v29
	v_max_f32_e32 v30, v30, v30
	v_max_f32_e32 v30, 0, v30
	v_mul_f32_e32 v30, v30, v30
	v_max_f32_e32 v31, v31, v31
	v_max_f32_e32 v31, 0, v31
	v_mul_f32_e32 v31, v31, v31
	v_max_f32_e32 v24, v24, v24
	v_max_f32_e32 v24, 0, v24
	v_mul_f32_e32 v24, v24, v24
	v_max_f32_e32 v25, v25, v25
	v_max_f32_e32 v25, 0, v25
	v_mul_f32_e32 v25, v25, v25
	v_max_f32_e32 v26, v26, v26
	v_max_f32_e32 v26, 0, v26
	v_mul_f32_e32 v26, v26, v26
	v_max_f32_e32 v27, v27, v27
	v_max_f32_e32 v27, 0, v27
	v_mul_f32_e32 v27, v27, v27
	v_cvt_pk_bf16_f32 v230, v28, v29
	v_cvt_pk_bf16_f32 v231, v30, v31
	v_cvt_pk_bf16_f32 v232, v24, v25
	v_cvt_pk_bf16_f32 v233, v26, v27
	v_add_co_u32_e32 v246, vcc, 0x140000, v244
	v_addc_co_u32_e32 v247, vcc, 0, v245, vcc
	v_permlane16_swap_b32 v230, v232
	v_permlane16_swap_b32 v231, v233
	global_store_dwordx4 v[246:247], v[230:233], off
	v_max_f32_e32 v20, v20, v20
	v_max_f32_e32 v20, 0, v20
	v_mul_f32_e32 v20, v20, v20
	v_max_f32_e32 v21, v21, v21
	v_max_f32_e32 v21, 0, v21
	v_mul_f32_e32 v21, v21, v21
	v_max_f32_e32 v22, v22, v22
	v_max_f32_e32 v22, 0, v22
	v_mul_f32_e32 v22, v22, v22
	v_max_f32_e32 v23, v23, v23
	v_max_f32_e32 v23, 0, v23
	v_mul_f32_e32 v23, v23, v23
	v_max_f32_e32 v16, v16, v16
	v_max_f32_e32 v16, 0, v16
	v_mul_f32_e32 v16, v16, v16
	v_max_f32_e32 v17, v17, v17
	v_max_f32_e32 v17, 0, v17
	v_mul_f32_e32 v17, v17, v17
	v_max_f32_e32 v18, v18, v18
	v_max_f32_e32 v18, 0, v18
	v_mul_f32_e32 v18, v18, v18
	v_max_f32_e32 v19, v19, v19
	v_max_f32_e32 v19, 0, v19
	v_mul_f32_e32 v19, v19, v19
	v_cvt_pk_bf16_f32 v234, v20, v21
	v_cvt_pk_bf16_f32 v235, v22, v23
	v_cvt_pk_bf16_f32 v236, v16, v17
	v_cvt_pk_bf16_f32 v237, v18, v19
	v_add_co_u32_e32 v246, vcc, 0x140100, v244
	v_addc_co_u32_e32 v247, vcc, 0, v245, vcc
	v_permlane16_swap_b32 v234, v236
	v_permlane16_swap_b32 v235, v237
	global_store_dwordx4 v[246:247], v[234:237], off
	v_max_f32_e32 v12, v12, v12
	v_max_f32_e32 v12, 0, v12
	v_mul_f32_e32 v12, v12, v12
	v_max_f32_e32 v13, v13, v13
	v_max_f32_e32 v13, 0, v13
	v_mul_f32_e32 v13, v13, v13
	v_max_f32_e32 v14, v14, v14
	v_max_f32_e32 v14, 0, v14
	v_mul_f32_e32 v14, v14, v14
	v_max_f32_e32 v15, v15, v15
	v_max_f32_e32 v15, 0, v15
	v_mul_f32_e32 v15, v15, v15
	v_max_f32_e32 v8, v8, v8
	v_max_f32_e32 v8, 0, v8
	v_mul_f32_e32 v8, v8, v8
	v_max_f32_e32 v9, v9, v9
	v_max_f32_e32 v9, 0, v9
	v_mul_f32_e32 v9, v9, v9
	v_max_f32_e32 v10, v10, v10
	v_max_f32_e32 v10, 0, v10
	v_mul_f32_e32 v10, v10, v10
	v_max_f32_e32 v11, v11, v11
	v_max_f32_e32 v11, 0, v11
	v_mul_f32_e32 v11, v11, v11
	v_cvt_pk_bf16_f32 v230, v12, v13
	v_cvt_pk_bf16_f32 v231, v14, v15
	v_cvt_pk_bf16_f32 v232, v8, v9
	v_cvt_pk_bf16_f32 v233, v10, v11
	v_add_co_u32_e32 v246, vcc, 0x160000, v244
	v_addc_co_u32_e32 v247, vcc, 0, v245, vcc
	v_permlane16_swap_b32 v230, v232
	v_permlane16_swap_b32 v231, v233
	global_store_dwordx4 v[246:247], v[230:233], off
	v_max_f32_e32 v4, v4, v4
	v_max_f32_e32 v4, 0, v4
	v_mul_f32_e32 v4, v4, v4
	v_max_f32_e32 v5, v5, v5
	v_max_f32_e32 v5, 0, v5
	v_mul_f32_e32 v5, v5, v5
	v_max_f32_e32 v6, v6, v6
	v_max_f32_e32 v6, 0, v6
	v_mul_f32_e32 v6, v6, v6
	v_max_f32_e32 v7, v7, v7
	v_max_f32_e32 v7, 0, v7
	v_mul_f32_e32 v7, v7, v7
	v_max_f32_e32 v0, v0, v0
	v_max_f32_e32 v0, 0, v0
	v_mul_f32_e32 v0, v0, v0
	v_max_f32_e32 v1, v1, v1
	v_max_f32_e32 v1, 0, v1
	v_mul_f32_e32 v1, v1, v1
	v_max_f32_e32 v2, v2, v2
	v_max_f32_e32 v2, 0, v2
	v_mul_f32_e32 v2, v2, v2
	v_max_f32_e32 v3, v3, v3
	v_max_f32_e32 v3, 0, v3
	v_mul_f32_e32 v3, v3, v3
	v_cvt_pk_bf16_f32 v234, v4, v5
	v_cvt_pk_bf16_f32 v235, v6, v7
	v_cvt_pk_bf16_f32 v236, v0, v1
	v_cvt_pk_bf16_f32 v237, v2, v3
	v_add_co_u32_e32 v246, vcc, 0x160100, v244
	v_addc_co_u32_e32 v247, vcc, 0, v245, vcc
	v_permlane16_swap_b32 v234, v236
	v_permlane16_swap_b32 v235, v237
	global_store_dwordx4 v[246:247], v[234:237], off
	s_branch .LBB0_1065

.LBB0_1065:
	s_and_b64 vcc, exec, s[6:7]
	s_mov_b64 s[2:3], -1
	s_mov_b32 s54, 0xb000
	s_mov_b32 s55, 0x16000
	s_cbranch_vccnz .LBB0_79
	v_readlane_b32 s2, v254, 52
	v_readlane_b32 s3, v254, 53
	s_andn2_b64 vcc, exec, s[2:3]
	s_cbranch_vccnz .LBB0_78
	s_barrier
	s_branch .LBB0_78
.Ltramp_1290:
	s_branch .LBB0_1290
